# in-proj K-loop: per-MFMA-group priority raise removed (load half-interval is the longer one)
# baseline (speedup 1.0000x reference)
.LBB0_104:
	s_add_u32 s6, s4, 0x100
	s_addc_u32 s7, s5, 0
	s_add_i32 s39, 0, 0x10000
	v_add_u32_e32 v140, s39, v168
	v_add_u32_e32 v144, s39, v169
	ds_read_b128 v[140:143], v140
	ds_read_b128 v[144:147], v144
	ds_read_b128 v[148:151], v173
	ds_read_b128 v[152:155], v174
	s_cmp_eq_u32 s38, 12
	s_cselect_b32 s17, s9, s7
	s_cselect_b32 s16, s34, s6
	s_cselect_b32 s15, s3, s37
	s_cselect_b32 s14, s35, s36
	v_lshl_add_u64 v[160:161], s[4:5], 0, v[136:137]
	s_add_i32 m0, s22, 0xc000
	ds_read_b128 v[156:159], v175
	ds_read_b128 v[198:201], v175 offset:2048
	ds_read_b128 v[202:205], v176
	ds_read_b128 v[206:209], v176 offset:2048
	ds_read_b128 v[210:213], v175 offset:4096
	ds_read_b128 v[214:217], v175 offset:6144
	ds_read_b128 v[218:221], v176 offset:4096
	ds_read_b128 v[222:225], v176 offset:6144
	global_load_lds_dwordx4 v[160:161], off
	v_lshl_add_u64 v[160:161], s[4:5], 0, v[138:139]
	s_add_i32 m0, s22, 0xe000
	s_nop 0
	global_load_lds_dwordx4 v[160:161], off
	s_waitcnt lgkmcnt(8)
	s_barrier
	s_waitcnt lgkmcnt(0)
	s_setprio 0
	s_waitcnt lgkmcnt(0)
	v_mfma_f32_16x16x32_bf16 v[126:129], v[140:143], v[156:159], v[126:129]
	v_mfma_f32_16x16x32_bf16 v[122:125], v[148:151], v[156:159], v[122:125]
	v_mfma_f32_16x16x32_bf16 v[110:113], v[140:143], v[198:201], v[110:113]
	v_mfma_f32_16x16x32_bf16 v[106:109], v[148:151], v[198:201], v[106:109]
	v_mfma_f32_16x16x32_bf16 v[94:97], v[140:143], v[210:213], v[94:97]
	v_mfma_f32_16x16x32_bf16 v[90:93], v[148:151], v[210:213], v[90:93]
	v_mfma_f32_16x16x32_bf16 v[78:81], v[140:143], v[214:217], v[78:81]
	v_mfma_f32_16x16x32_bf16 v[74:77], v[148:151], v[214:217], v[74:77]
	v_mfma_f32_16x16x32_bf16 v[126:129], v[144:147], v[202:205], v[126:129]
	v_mfma_f32_16x16x32_bf16 v[122:125], v[152:155], v[202:205], v[122:125]
	v_mfma_f32_16x16x32_bf16 v[110:113], v[144:147], v[206:209], v[110:113]
	v_mfma_f32_16x16x32_bf16 v[106:109], v[152:155], v[206:209], v[106:109]
	v_mfma_f32_16x16x32_bf16 v[94:97], v[144:147], v[218:221], v[94:97]
	v_mfma_f32_16x16x32_bf16 v[90:93], v[152:155], v[218:221], v[90:93]
	v_mfma_f32_16x16x32_bf16 v[78:81], v[144:147], v[222:225], v[78:81]
	v_mfma_f32_16x16x32_bf16 v[74:77], v[152:155], v[222:225], v[74:77]
	s_setprio 0
	s_barrier
	s_add_i32 s40, 0, 0x14000
	v_add_u32_e32 v160, s40, v168
	v_add_u32_e32 v161, s40, v169
	s_add_i32 s4, s39, s21
	ds_read_b128 v[226:229], v160
	ds_read_b128 v[230:233], v161
	ds_read_b128 v[234:237], v177
	ds_read_b128 v[238:241], v178
	v_lshl_add_u64 v[160:161], s[14:15], 0, v[132:133]
	s_mov_b32 m0, s4
	v_lshl_add_u64 v[166:167], s[14:15], 0, v[130:131]
	global_load_lds_dwordx4 v[160:161], off
	s_add_i32 m0, s4, 0x2000
	s_nop 0
	global_load_lds_dwordx4 v[166:167], off
	s_barrier
	s_waitcnt lgkmcnt(0)
	s_setprio 0
	s_waitcnt lgkmcnt(0)
	v_mfma_f32_16x16x32_bf16 v[118:121], v[226:229], v[156:159], v[118:121]
	v_mfma_f32_16x16x32_bf16 v[114:117], v[234:237], v[156:159], v[114:117]
	v_mfma_f32_16x16x32_bf16 v[102:105], v[226:229], v[198:201], v[102:105]
	v_mfma_f32_16x16x32_bf16 v[98:101], v[234:237], v[198:201], v[98:101]
	v_mfma_f32_16x16x32_bf16 v[86:89], v[226:229], v[210:213], v[86:89]
	v_mfma_f32_16x16x32_bf16 v[82:85], v[234:237], v[210:213], v[82:85]
	v_mfma_f32_16x16x32_bf16 v[70:73], v[226:229], v[214:217], v[70:73]
	v_mfma_f32_16x16x32_bf16 v[66:69], v[234:237], v[214:217], v[66:69]
	v_mfma_f32_16x16x32_bf16 v[118:121], v[230:233], v[202:205], v[118:121]
	v_mfma_f32_16x16x32_bf16 v[114:117], v[238:241], v[202:205], v[114:117]
	v_mfma_f32_16x16x32_bf16 v[102:105], v[230:233], v[206:209], v[102:105]
	v_mfma_f32_16x16x32_bf16 v[98:101], v[238:241], v[206:209], v[98:101]
	v_mfma_f32_16x16x32_bf16 v[86:89], v[230:233], v[218:221], v[86:89]
	v_mfma_f32_16x16x32_bf16 v[82:85], v[238:241], v[218:221], v[82:85]
	v_mfma_f32_16x16x32_bf16 v[70:73], v[230:233], v[222:225], v[70:73]
	v_mfma_f32_16x16x32_bf16 v[66:69], v[238:241], v[222:225], v[66:69]
	s_setprio 0
	s_mov_b32 m0, s22
	v_lshl_add_u64 v[242:243], s[16:17], 0, v[132:133]
	s_barrier
	ds_read_b128 v[156:159], v175 offset:16384
	ds_read_b128 v[198:201], v175 offset:18432
	ds_read_b128 v[202:205], v176 offset:16384
	ds_read_b128 v[206:209], v176 offset:18432
	ds_read_b128 v[210:213], v175 offset:20480
	ds_read_b128 v[214:217], v175 offset:22528
	ds_read_b128 v[218:221], v176 offset:20480
	ds_read_b128 v[222:225], v176 offset:22528
	global_load_lds_dwordx4 v[242:243], off
	v_lshl_add_u64 v[244:245], s[16:17], 0, v[130:131]
	s_mov_b32 m0, s23
	s_nop 0
	global_load_lds_dwordx4 v[244:245], off
	s_barrier
	s_waitcnt lgkmcnt(0)
	s_setprio 0
	s_waitcnt lgkmcnt(0)
	v_mfma_f32_16x16x32_bf16 v[62:65], v[140:143], v[156:159], v[62:65]
	v_mfma_f32_16x16x32_bf16 v[58:61], v[148:151], v[156:159], v[58:61]
	v_mfma_f32_16x16x32_bf16 v[46:49], v[140:143], v[198:201], v[46:49]
	v_mfma_f32_16x16x32_bf16 v[42:45], v[148:151], v[198:201], v[42:45]
	v_mfma_f32_16x16x32_bf16 v[30:33], v[140:143], v[210:213], v[30:33]
	v_mfma_f32_16x16x32_bf16 v[26:29], v[148:151], v[210:213], v[26:29]
	v_mfma_f32_16x16x32_bf16 v[14:17], v[140:143], v[214:217], v[14:17]
	v_mfma_f32_16x16x32_bf16 v[10:13], v[148:151], v[214:217], v[10:13]
	v_mfma_f32_16x16x32_bf16 v[62:65], v[144:147], v[202:205], v[62:65]
	v_mfma_f32_16x16x32_bf16 v[58:61], v[152:155], v[202:205], v[58:61]
	v_mfma_f32_16x16x32_bf16 v[46:49], v[144:147], v[206:209], v[46:49]
	v_mfma_f32_16x16x32_bf16 v[42:45], v[152:155], v[206:209], v[42:45]
	v_mfma_f32_16x16x32_bf16 v[30:33], v[144:147], v[218:221], v[30:33]
	v_mfma_f32_16x16x32_bf16 v[26:29], v[152:155], v[218:221], v[26:29]
	v_mfma_f32_16x16x32_bf16 v[14:17], v[144:147], v[222:225], v[14:17]
	v_mfma_f32_16x16x32_bf16 v[10:13], v[152:155], v[222:225], v[10:13]
	s_setprio 0
	s_barrier
	s_add_u32 s4, s14, 0x40000
	s_addc_u32 s5, s15, 0
	s_add_i32 s39, s40, s21
	v_lshl_add_u64 v[140:141], s[4:5], 0, v[132:133]
	s_mov_b32 m0, s39
	s_nop 0
	global_load_lds_dwordx4 v[140:141], off
	v_lshl_add_u64 v[140:141], s[4:5], 0, v[130:131]
	s_add_i32 m0, s39, 0x2000
	s_nop 0
	global_load_lds_dwordx4 v[140:141], off
	s_waitcnt vmcnt(6)
	s_barrier
	s_setprio 0
	v_mfma_f32_16x16x32_bf16 v[54:57], v[226:229], v[156:159], v[54:57]
	v_mfma_f32_16x16x32_bf16 v[50:53], v[234:237], v[156:159], v[50:53]
	v_mfma_f32_16x16x32_bf16 v[38:41], v[226:229], v[198:201], v[38:41]
	v_mfma_f32_16x16x32_bf16 v[34:37], v[234:237], v[198:201], v[34:37]
	v_mfma_f32_16x16x32_bf16 v[22:25], v[226:229], v[210:213], v[22:25]
	v_mfma_f32_16x16x32_bf16 v[18:21], v[234:237], v[210:213], v[18:21]
	v_mfma_f32_16x16x32_bf16 v[6:9], v[226:229], v[214:217], v[6:9]
	v_mfma_f32_16x16x32_bf16 v[2:5], v[234:237], v[214:217], v[2:5]
	v_mfma_f32_16x16x32_bf16 v[54:57], v[230:233], v[202:205], v[54:57]
	v_mfma_f32_16x16x32_bf16 v[50:53], v[238:241], v[202:205], v[50:53]
	v_mfma_f32_16x16x32_bf16 v[38:41], v[230:233], v[206:209], v[38:41]
	v_mfma_f32_16x16x32_bf16 v[34:37], v[238:241], v[206:209], v[34:37]
	v_mfma_f32_16x16x32_bf16 v[22:25], v[230:233], v[218:221], v[22:25]
	v_mfma_f32_16x16x32_bf16 v[18:21], v[238:241], v[218:221], v[18:21]
	v_mfma_f32_16x16x32_bf16 v[6:9], v[230:233], v[222:225], v[6:9]
	v_mfma_f32_16x16x32_bf16 v[2:5], v[238:241], v[222:225], v[2:5]
	s_setprio 0
	s_add_i32 s39, 0, 0x18000
	v_add_u32_e32 v140, s39, v168
	v_add_u32_e32 v144, s39, v169
	s_barrier
	ds_read_b128 v[140:143], v140
	ds_read_b128 v[144:147], v144
	ds_read_b128 v[148:151], v179
	ds_read_b128 v[152:155], v180
	s_add_u32 s4, s16, 0x40000
	s_addc_u32 s5, s17, 0
	s_mov_b32 m0, s24
	v_lshl_add_u64 v[226:227], s[4:5], 0, v[132:133]
	ds_read_b128 v[156:159], v175 offset:32768
	ds_read_b128 v[198:201], v175 offset:34816
	ds_read_b128 v[202:205], v176 offset:32768
	ds_read_b128 v[206:209], v176 offset:34816
	ds_read_b128 v[210:213], v175 offset:36864
	ds_read_b128 v[214:217], v175 offset:38912
	ds_read_b128 v[218:221], v176 offset:36864
	ds_read_b128 v[222:225], v176 offset:38912
	global_load_lds_dwordx4 v[226:227], off
	v_lshl_add_u64 v[226:227], s[4:5], 0, v[130:131]
	s_mov_b32 m0, s25
	s_nop 0
	global_load_lds_dwordx4 v[226:227], off
	s_waitcnt lgkmcnt(8)
	s_barrier
	s_waitcnt lgkmcnt(0)
	s_setprio 0
	s_waitcnt lgkmcnt(0)
	v_mfma_f32_16x16x32_bf16 v[126:129], v[140:143], v[156:159], v[126:129]
	v_mfma_f32_16x16x32_bf16 v[122:125], v[148:151], v[156:159], v[122:125]
	v_mfma_f32_16x16x32_bf16 v[110:113], v[140:143], v[198:201], v[110:113]
	v_mfma_f32_16x16x32_bf16 v[106:109], v[148:151], v[198:201], v[106:109]
	v_mfma_f32_16x16x32_bf16 v[94:97], v[140:143], v[210:213], v[94:97]
	v_mfma_f32_16x16x32_bf16 v[90:93], v[148:151], v[210:213], v[90:93]
	v_mfma_f32_16x16x32_bf16 v[78:81], v[140:143], v[214:217], v[78:81]
	v_mfma_f32_16x16x32_bf16 v[74:77], v[148:151], v[214:217], v[74:77]
	v_mfma_f32_16x16x32_bf16 v[126:129], v[144:147], v[202:205], v[126:129]
	v_mfma_f32_16x16x32_bf16 v[122:125], v[152:155], v[202:205], v[122:125]
	v_mfma_f32_16x16x32_bf16 v[110:113], v[144:147], v[206:209], v[110:113]
	v_mfma_f32_16x16x32_bf16 v[106:109], v[152:155], v[206:209], v[106:109]
	v_mfma_f32_16x16x32_bf16 v[94:97], v[144:147], v[218:221], v[94:97]
	v_mfma_f32_16x16x32_bf16 v[90:93], v[152:155], v[218:221], v[90:93]
	v_mfma_f32_16x16x32_bf16 v[78:81], v[144:147], v[222:225], v[78:81]
	v_mfma_f32_16x16x32_bf16 v[74:77], v[152:155], v[222:225], v[74:77]
	s_setprio 0
	s_barrier
	s_add_i32 s16, 0, 0x1c000
	s_add_i32 s4, s39, s21
	v_add_u32_e32 v186, s16, v168
	v_lshl_add_u64 v[160:161], v[160:161], 0, s[42:43]
	s_mov_b32 m0, s4
	v_add_u32_e32 v187, s16, v169
	ds_read_b128 v[226:229], v186
	ds_read_b128 v[230:233], v187
	ds_read_b128 v[234:237], v181
	ds_read_b128 v[238:241], v197
	global_load_lds_dwordx4 v[160:161], off
	v_lshl_add_u64 v[160:161], v[166:167], 0, s[42:43]
	s_add_i32 m0, s4, 0x2000
	s_nop 0
	global_load_lds_dwordx4 v[160:161], off
	s_barrier
	s_waitcnt lgkmcnt(0)
	s_setprio 0
	s_waitcnt lgkmcnt(0)
	v_mfma_f32_16x16x32_bf16 v[118:121], v[226:229], v[156:159], v[118:121]
	v_mfma_f32_16x16x32_bf16 v[114:117], v[234:237], v[156:159], v[114:117]
	v_mfma_f32_16x16x32_bf16 v[102:105], v[226:229], v[198:201], v[102:105]
	v_mfma_f32_16x16x32_bf16 v[98:101], v[234:237], v[198:201], v[98:101]
	v_mfma_f32_16x16x32_bf16 v[86:89], v[226:229], v[210:213], v[86:89]
	v_mfma_f32_16x16x32_bf16 v[82:85], v[234:237], v[210:213], v[82:85]
	v_mfma_f32_16x16x32_bf16 v[70:73], v[226:229], v[214:217], v[70:73]
	v_mfma_f32_16x16x32_bf16 v[66:69], v[234:237], v[214:217], v[66:69]
	v_mfma_f32_16x16x32_bf16 v[118:121], v[230:233], v[202:205], v[118:121]
	v_mfma_f32_16x16x32_bf16 v[114:117], v[238:241], v[202:205], v[114:117]
	v_mfma_f32_16x16x32_bf16 v[102:105], v[230:233], v[206:209], v[102:105]
	v_mfma_f32_16x16x32_bf16 v[98:101], v[238:241], v[206:209], v[98:101]
	v_mfma_f32_16x16x32_bf16 v[86:89], v[230:233], v[218:221], v[86:89]
	v_mfma_f32_16x16x32_bf16 v[82:85], v[238:241], v[218:221], v[82:85]
	v_mfma_f32_16x16x32_bf16 v[70:73], v[230:233], v[222:225], v[70:73]
	v_mfma_f32_16x16x32_bf16 v[66:69], v[238:241], v[222:225], v[66:69]
	s_setprio 0
	s_mov_b32 m0, s27
	v_lshl_add_u64 v[160:161], v[242:243], 0, s[42:43]
	s_barrier
	ds_read_b128 v[156:159], v175 offset:49152
	ds_read_b128 v[198:201], v175 offset:51200
	ds_read_b128 v[202:205], v176 offset:49152
	ds_read_b128 v[206:209], v176 offset:51200
	ds_read_b128 v[210:213], v175 offset:53248
	ds_read_b128 v[214:217], v175 offset:55296
	ds_read_b128 v[218:221], v176 offset:53248
	ds_read_b128 v[222:225], v176 offset:55296
	global_load_lds_dwordx4 v[160:161], off
	v_lshl_add_u64 v[160:161], v[244:245], 0, s[42:43]
	s_mov_b32 m0, s28
	s_nop 0
	global_load_lds_dwordx4 v[160:161], off
	s_barrier
	s_waitcnt lgkmcnt(0)
	s_setprio 0
	s_waitcnt lgkmcnt(0)
	v_mfma_f32_16x16x32_bf16 v[62:65], v[140:143], v[156:159], v[62:65]
	v_mfma_f32_16x16x32_bf16 v[58:61], v[148:151], v[156:159], v[58:61]
	v_mfma_f32_16x16x32_bf16 v[46:49], v[140:143], v[198:201], v[46:49]
	v_mfma_f32_16x16x32_bf16 v[42:45], v[148:151], v[198:201], v[42:45]
	v_mfma_f32_16x16x32_bf16 v[30:33], v[140:143], v[210:213], v[30:33]
	v_mfma_f32_16x16x32_bf16 v[26:29], v[148:151], v[210:213], v[26:29]
	v_mfma_f32_16x16x32_bf16 v[14:17], v[140:143], v[214:217], v[14:17]
	v_mfma_f32_16x16x32_bf16 v[10:13], v[148:151], v[214:217], v[10:13]
	v_mfma_f32_16x16x32_bf16 v[62:65], v[144:147], v[202:205], v[62:65]
	v_mfma_f32_16x16x32_bf16 v[58:61], v[152:155], v[202:205], v[58:61]
	v_mfma_f32_16x16x32_bf16 v[46:49], v[144:147], v[206:209], v[46:49]
	v_mfma_f32_16x16x32_bf16 v[42:45], v[152:155], v[206:209], v[42:45]
	v_mfma_f32_16x16x32_bf16 v[30:33], v[144:147], v[218:221], v[30:33]
	v_mfma_f32_16x16x32_bf16 v[26:29], v[152:155], v[218:221], v[26:29]
	v_mfma_f32_16x16x32_bf16 v[14:17], v[144:147], v[222:225], v[14:17]
	v_mfma_f32_16x16x32_bf16 v[10:13], v[152:155], v[222:225], v[10:13]
	s_setprio 0
	s_barrier
	s_add_u32 s4, s14, 0x40080
	s_addc_u32 s5, s15, 0
	s_add_i32 s14, s16, s21
	v_lshl_add_u64 v[140:141], s[4:5], 0, v[132:133]
	s_mov_b32 m0, s14
	s_nop 0
	global_load_lds_dwordx4 v[140:141], off
	v_lshl_add_u64 v[140:141], s[4:5], 0, v[130:131]
	s_add_i32 m0, s14, 0x2000
	s_nop 0
	global_load_lds_dwordx4 v[140:141], off
	s_waitcnt vmcnt(6)
	s_barrier
	s_setprio 0
	v_mfma_f32_16x16x32_bf16 v[54:57], v[226:229], v[156:159], v[54:57]
	v_mfma_f32_16x16x32_bf16 v[50:53], v[234:237], v[156:159], v[50:53]
	v_mfma_f32_16x16x32_bf16 v[38:41], v[226:229], v[198:201], v[38:41]
	v_mfma_f32_16x16x32_bf16 v[34:37], v[234:237], v[198:201], v[34:37]
	v_mfma_f32_16x16x32_bf16 v[22:25], v[226:229], v[210:213], v[22:25]
	v_mfma_f32_16x16x32_bf16 v[18:21], v[234:237], v[210:213], v[18:21]
	v_mfma_f32_16x16x32_bf16 v[6:9], v[226:229], v[214:217], v[6:9]
	v_mfma_f32_16x16x32_bf16 v[2:5], v[234:237], v[214:217], v[2:5]
	v_mfma_f32_16x16x32_bf16 v[54:57], v[230:233], v[202:205], v[54:57]
	v_mfma_f32_16x16x32_bf16 v[50:53], v[238:241], v[202:205], v[50:53]
	v_mfma_f32_16x16x32_bf16 v[38:41], v[230:233], v[206:209], v[38:41]
	v_mfma_f32_16x16x32_bf16 v[34:37], v[238:241], v[206:209], v[34:37]
	v_mfma_f32_16x16x32_bf16 v[22:25], v[230:233], v[218:221], v[22:25]
	v_mfma_f32_16x16x32_bf16 v[18:21], v[238:241], v[218:221], v[18:21]
	v_mfma_f32_16x16x32_bf16 v[6:9], v[230:233], v[222:225], v[6:9]
	v_mfma_f32_16x16x32_bf16 v[2:5], v[238:241], v[222:225], v[2:5]
	s_setprio 0
	s_add_i32 s38, s38, 2
	s_add_u32 s36, s36, 0x100
	s_addc_u32 s37, s37, 0
	s_cmp_gt_u32 s38, 13
	s_mov_b64 s[4:5], s[6:7]
	s_barrier
	s_cbranch_scc0 .LBB0_104
	s_lshl_b32 s9, s31, 8
	v_add_u32_e32 v144, s9, v1
	v_ashrrev_i32_e32 v145, 31, v144
	v_lshl_add_u64 v[140:141], v[144:145], 2, s[56:57]
	global_load_dword v160, v[140:141], off
	global_load_dword v156, v[140:141], off offset:64
	global_load_dword v154, v[140:141], off offset:128
	global_load_dword v152, v[140:141], off offset:192
	global_load_dword v150, v[140:141], off offset:512
	global_load_dword v148, v[140:141], off offset:576
	global_load_dword v146, v[140:141], off offset:640
	s_nop 0
	global_load_dword v140, v[140:141], off offset:704
	s_lshl_b32 s3, s30, 8
	s_or_b32 s14, s3, s26
	v_or_b32_e32 v142, s14, v134
	s_movk_i32 s3, 0xeff
	v_lshlrev_b64 v[158:159], 5, v[144:145]
	v_cmp_lt_i32_e64 s[4:5], s3, v142
	s_waitcnt vmcnt(0)
	v_pk_mul_f32 v[128:129], v[128:129], v[160:161] op_sel_hi:[1,0]
	v_pk_mul_f32 v[126:127], v[126:127], v[160:161] op_sel_hi:[1,0]
	v_pk_mul_f32 v[124:125], v[124:125], v[160:161] op_sel_hi:[1,0]
	v_pk_mul_f32 v[122:123], v[122:123], v[160:161] op_sel_hi:[1,0]
	s_and_saveexec_b64 s[6:7], s[4:5]
	s_xor_b64 s[6:7], exec, s[6:7]
	s_cbranch_execz .LBB0_108
	s_cmpk_gt_u32 s14, 0xf1f
	s_cbranch_scc1 .LBB0_108
	v_lshl_add_u64 v[166:167], v[158:159], 2, s[60:61]
	v_mov_b32_e32 v143, v0
	v_lshl_add_u64 v[166:167], v[142:143], 2, v[166:167]
	v_add_co_u32_e32 v166, vcc, 0xffffd000, v166
	s_nop 1
	v_addc_co_u32_e32 v167, vcc, -1, v167, vcc
	global_store_dwordx4 v[166:167], v[126:129], off offset:-3072
	global_store_dwordx4 v[166:167], v[122:125], off offset:-3056
